# walk phases: static s_setprio 1 for the half-workgroup that starts first for the whole job, per-segment toggles replaced by s_nop; on top of static GEMM priority
# baseline (speedup 1.0000x reference)
.LBB0_443:
	v_mov_b32_e32 v33, v1
	v_lshl_add_u64 v[2:3], v[2:3], 1, v[40:41]
	v_lshl_add_u64 v[40:41], s[68:69], 0, v[32:33]
	v_lshl_add_u64 v[32:33], s[70:71], 0, v[0:1]
	s_movk_i32 s10, 0xffbe
	v_lshl_add_u64 v[32:33], v[46:47], 1, v[32:33]
	v_mov_b32_e32 v49, v1
	v_mul_lo_u32 v0, v186, s10
	s_movk_i32 s10, 0x840
	v_mul_u32_u24_e32 v55, 0x84, v42
	v_add_u32_e32 v56, 0x41, v84
	v_lshl_add_u64 v[42:43], v[34:35], 1, v[68:69]
	v_lshl_add_u64 v[44:45], v[44:45], 1, s[84:85]
	v_lshl_add_u64 v[46:47], v[32:33], 0, v[48:49]
	v_mul_lo_u32 v57, v186, s10
	s_mov_b64 s[10:11], 0
	s_waitcnt vmcnt(0)
	v_mov_b64_e32 v[48:49], v[28:29]
	v_mov_b64_e32 v[50:51], v[30:31]
	v_readfirstlane_b32 s19, v65
	s_cmp_eq_u32 s19, 1
	s_setprio 1
	s_cbranch_scc0 .Lwoff_gla_a
	s_barrier
	s_setprio 0

.LBB0_444:
	s_or_b64 exec, exec, s[14:15]
	s_nop 0
	v_add_u32_e32 v0, -1, v0
	v_mov_b32_e32 v84, v83
	s_andn2_b64 exec, exec, s[10:11]
	s_cbranch_execz .LBB0_474

.LBB0_470:
	s_or_b64 exec, exec, s[14:15]
	s_waitcnt lgkmcnt(0)
	s_barrier
	s_and_b64 s[14:15], exec, s[64:65]
	s_or_b64 s[10:11], s[14:15], s[10:11]
	s_nop 0
	v_and_b32_e32 v33, 32, v57
	s_movk_i32 s14, 0x90
	v_mad_u32_u24 v33, v33, s14, v175
	s_and_b64 vcc, exec, s[46:47]
	s_cbranch_vccz .Lgb_k1
	s_and_b64 vcc, exec, s[62:63]
	s_cbranch_vccnz .Lgb_m0k2
	ds_read_b128 v[188:191], v132
	ds_read_b128 v[84:87], v33 offset:23552
	ds_read_b128 v[88:91], v33 offset:25856
	ds_read_b128 v[192:195], v132 offset:64
	ds_read_b128 v[92:95], v33 offset:23616
	ds_read_b128 v[196:199], v33 offset:25920
	ds_read_b64_tr_b16 v[200:201], v133 offset:18432
	ds_read_b64_tr_b16 v[202:203], v133 offset:18752
	ds_read_b64_tr_b16 v[238:239], v140 offset:9216
	ds_read_b64_tr_b16 v[240:241], v140 offset:9792
	ds_read_b64_tr_b16 v[234:235], v134 offset:18432
	ds_read_b64_tr_b16 v[236:237], v134 offset:18752
	ds_read_b64_tr_b16 v[242:243], v141 offset:9216
	ds_read_b64_tr_b16 v[244:245], v141 offset:9792
	ds_read_b32 v204, v143 offset:32768
	v_lshlrev_b32_e32 v34, 16, v30
	v_and_b32_e32 v35, 0xffff0000, v30
	v_lshlrev_b32_e32 v96, 16, v31
	v_and_b32_e32 v97, 0xffff0000, v31
	v_lshlrev_b32_e32 v98, 16, v28
	v_and_b32_e32 v99, 0xffff0000, v28
	v_lshlrev_b32_e32 v100, 16, v29
	v_and_b32_e32 v101, 0xffff0000, v29
	v_add_u32_e32 v32, v32, v54
	v_mad_i64_i32 v[32:33], s[14:15], v32, s16, v[2:3]
	s_waitcnt lgkmcnt(12)
	v_mfma_f32_16x16x32_bf16 v[84:87], v[84:87], v[188:191], 0
	v_mfma_f32_16x16x32_bf16 v[88:91], v[88:91], v[188:191], 0
	s_waitcnt lgkmcnt(9)
	v_mfma_f32_16x16x32_bf16 v[84:87], v[92:95], v[192:195], v[84:87]
	v_mfma_f32_16x16x32_bf16 v[88:91], v[196:199], v[192:195], v[88:91]
	ds_read_b64_tr_b16 v[246:247], v135 offset:9248
	ds_read_b64_tr_b16 v[248:249], v135 offset:9824
	ds_read_b64_tr_b16 v[250:251], v136 offset:9248
	ds_read_b64_tr_b16 v[252:253], v136 offset:9824
	ds_read_b32 v205, v144 offset:32832
	s_movk_i32 s14, 0x90
	v_add_u32_e32 v57, 32, v57
	v_and_b32_e32 v28, 32, v57
	v_mad_u32_u24 v28, v28, s14, v71
	v_lshlrev_b32_e32 v29, 1, v114
	v_lshlrev_b32_e32 v30, 1, v142
	v_add3_u32 v30, v28, v30, v29
	v_lshlrev_b32_e32 v31, 1, v112
	v_add3_u32 v31, v28, v31, v29
	s_waitcnt lgkmcnt(10)
	v_mfma_f32_16x16x32_bf16 v[8:11], v[200:203], v[238:241], v[8:11]
	s_waitcnt lgkmcnt(6)
	v_mfma_f32_16x16x32_bf16 v[8:11], v[234:237], v[242:245], v[8:11]
	s_waitcnt lgkmcnt(3)
	v_mfma_f32_16x16x32_bf16 v[4:7], v[200:203], v[246:249], v[4:7]
	s_waitcnt lgkmcnt(1)
	v_mfma_f32_16x16x32_bf16 v[4:7], v[234:237], v[250:253], v[4:7]
	v_add_f32_e32 v34, v84, v34
	v_add_f32_e32 v35, v85, v35
	v_add_f32_e32 v96, v86, v96
	v_add_f32_e32 v97, v87, v97
	v_add_f32_e32 v98, v88, v98
	v_add_f32_e32 v99, v89, v99
	v_add_f32_e32 v100, v90, v100
	v_add_f32_e32 v101, v91, v101
	v_cvt_pk_bf16_f32 v34, v34, v35
	v_cvt_pk_bf16_f32 v35, v96, v97
	v_cvt_pk_bf16_f32 v98, v98, v99
	v_cvt_pk_bf16_f32 v99, v100, v101
	global_store_dwordx2 v[32:33], v[34:35], off
	global_store_dwordx2 v[32:33], v[98:99], off offset:32
	v_mul_f32_e32 v204, 0x3fb8aa3b, v204
	v_exp_f32_e32 v204, v204
	s_waitcnt lgkmcnt(0)
	v_mul_f32_e32 v28, 0x3fb8aa3b, v205
	v_exp_f32_e32 v28, v28
	v_pk_mul_f32 v[10:11], v[10:11], v[204:205] op_sel_hi:[1,0]
	v_pk_mul_f32 v[8:9], v[8:9], v[204:205] op_sel_hi:[1,0]
	v_pk_mul_f32 v[6:7], v[6:7], v[28:29] op_sel_hi:[1,0]
	v_pk_mul_f32 v[4:5], v[4:5], v[28:29] op_sel_hi:[1,0]
	v_cvt_pk_bf16_f32 v29, v8, s0
	ds_write_b16 v30, v29 offset:23552
	v_cvt_pk_bf16_f32 v29, v9, s0
	ds_write_b16 v30, v29 offset:23696
	v_cvt_pk_bf16_f32 v29, v10, s0
	ds_write_b16 v30, v29 offset:23840
	v_cvt_pk_bf16_f32 v29, v11, s0
	ds_write_b16 v30, v29 offset:23984
	v_cvt_pk_bf16_f32 v29, v4, s0
	ds_write_b16 v31, v29 offset:23584
	v_cvt_pk_bf16_f32 v29, v5, s0
	ds_write_b16 v31, v29 offset:23728
	v_cvt_pk_bf16_f32 v29, v6, s0
	ds_write_b16 v31, v29 offset:23872
	v_cvt_pk_bf16_f32 v29, v7, s0
	ds_write_b16 v31, v29 offset:24016
	s_mov_b64 s[14:15], exec
	s_branch .LBB0_444

.Lwoff_gla_b:
	s_setprio 0
	s_and_b64 vcc, exec, s[28:29]
	s_cbranch_vccz .LBB0_476
	global_store_dwordx4 v[36:37], v[8:11], off
	global_store_dwordx4 v[36:37], v[4:7], off offset:16
	s_mov_b64 s[42:43], -1

.LBB0_511:
	v_or_b32_e32 v98, v46, v83
	s_movk_i32 s10, 0xffd4
	v_lshlrev_b32_e32 v46, 4, v98
	v_mov_b32_e32 v47, v1
	v_mul_lo_u32 v194, v186, s10
	s_movk_i32 s10, 0x580
	v_mul_u32_u24_e32 v192, 0x84, v53
	s_mov_b32 s18, 44
	v_add_u32_e32 v193, 44, v52
	v_mov_b32_e32 v99, v1
	v_lshl_add_u64 v[100:101], v[48:49], 1, v[50:51]
	v_lshl_add_u64 v[102:103], s[90:91], 0, v[46:47]
	v_mul_lo_u32 v195, v186, s10
	v_mov_b32_e32 v57, 0
	s_waitcnt vmcnt(0)
	v_mov_b32_e32 v91, v96
	v_mov_b64_e32 v[108:109], v[104:105]
	v_mov_b64_e32 v[110:111], v[106:107]
	v_readfirstlane_b32 s10, v65
	s_cmp_eq_u32 s10, 1
	s_setprio 1
	s_cbranch_scc0 .Lwoff_ml_a
	s_barrier
	s_setprio 0

.LBB0_544:
	s_or_b64 exec, exec, s[10:11]
	v_and_b32_e32 v50, 32, v195
	s_nop 0
	v_mad_u32_u24 v93, v50, s34, v176
	ds_read_b128 v[50:53], v93 offset:31744
	ds_read_b128 v[198:201], v93 offset:35072
	s_waitcnt lgkmcnt(2)
	ds_read_b128 v[46:49], v169
	s_mov_b64 s[10:11], 0
	s_waitcnt lgkmcnt(0)
	v_mfma_f32_16x16x32_bf16 v[50:53], v[50:53], v[46:49], 0
	v_mfma_f32_16x16x32_bf16 v[46:49], v[198:201], v[46:49], 0
	ds_read_b128 v[198:201], v169 offset:64
	ds_read_b128 v[202:205], v93 offset:31808
	s_waitcnt lgkmcnt(0)
	v_mfma_f32_16x16x32_bf16 v[50:53], v[202:205], v[198:201], v[50:53]
	ds_read_b128 v[202:205], v93 offset:35136
	s_waitcnt lgkmcnt(0)
	v_mfma_f32_16x16x32_bf16 v[198:201], v[202:205], v[198:201], v[46:49]
	ds_read_b128 v[202:205], v169 offset:128
	s_nop 1
	ds_read_b128 v[46:49], v93 offset:31872
	s_waitcnt lgkmcnt(0)
	v_mfma_f32_16x16x32_bf16 v[46:49], v[46:49], v[202:205], v[50:53]
	s_nop 2
	ds_read_b128 v[50:53], v93 offset:35200
	s_waitcnt lgkmcnt(0)
	v_mfma_f32_16x16x32_bf16 v[50:53], v[50:53], v[202:205], v[198:201]
.LBB0_545:
	s_and_b64 vcc, exec, s[10:11]
	s_cbranch_vccz .LBB0_547
	s_nop 0
	s_nop 4
	v_mov_b32_e32 v50, 0
	v_mov_b32_e32 v51, v50
	v_mov_b32_e32 v52, v50
	v_mov_b32_e32 v53, v50
	v_mov_b32_e32 v46, v50
	v_mov_b32_e32 v47, v50
	v_mov_b32_e32 v48, v50
	v_mov_b32_e32 v49, v50
.LBB0_547:
	s_nop 0
	ds_read_b64_tr_b16 v[198:199], v133 offset:26624
	ds_read_b64_tr_b16 v[200:201], v133 offset:26944
	ds_read_b64_tr_b16 v[202:203], v134 offset:26624
	ds_read_b64_tr_b16 v[204:205], v134 offset:26944
	ds_read_b64_tr_b16 v[234:235], v173 offset:13312
	ds_read_b64_tr_b16 v[236:237], v173 offset:14144
	ds_read_b64_tr_b16 v[238:239], v174 offset:13312
	ds_read_b64_tr_b16 v[240:241], v174 offset:14144
	s_waitcnt lgkmcnt(8)
	v_mov_b32_e32 v242, v56
	v_add_u32_e32 v195, 32, v195
	v_and_b32_e32 v93, 32, v195
	s_waitcnt lgkmcnt(2)
	v_mfma_f32_16x16x32_bf16 v[234:237], v[198:201], v[234:237], 0
	v_mad_u32_u24 v93, v93, s34, v177
	s_waitcnt lgkmcnt(0)
	v_mfma_f32_16x16x32_bf16 v[234:237], v[202:205], v[238:241], v[234:237]
	s_nop 7
	v_pk_mul_f32 v[234:235], v[242:243], v[234:235] op_sel_hi:[0,1]
	v_pk_mul_f32 v[236:237], v[242:243], v[236:237] op_sel_hi:[0,1]
	v_pk_fma_f32 v[10:11], v[10:11], v[54:55], v[234:235] op_sel_hi:[1,0,1]
	v_pk_fma_f32 v[12:13], v[12:13], v[54:55], v[236:237] op_sel_hi:[1,0,1]
	v_cvt_pk_bf16_f32 v95, v10, s0
	v_cvt_pk_bf16_f32 v197, v11, s0
	ds_write_b16 v93, v95 offset:31744
	ds_write_b16 v93, v197 offset:31952
	v_cvt_pk_bf16_f32 v95, v12, s0
	ds_write_b16 v93, v95 offset:32160
	v_cvt_pk_bf16_f32 v95, v13, s0
	ds_write_b16 v93, v95 offset:32368
	ds_read_b64_tr_b16 v[234:235], v173 offset:13344
	ds_read_b64_tr_b16 v[236:237], v173 offset:14176
	ds_read_b64_tr_b16 v[238:239], v174 offset:13344
	ds_read_b64_tr_b16 v[240:241], v174 offset:14176
	s_waitcnt lgkmcnt(2)
	v_mfma_f32_16x16x32_bf16 v[234:237], v[198:201], v[234:237], 0
	s_waitcnt lgkmcnt(0)
	v_mfma_f32_16x16x32_bf16 v[234:237], v[202:205], v[238:241], v[234:237]
	s_nop 7
	v_pk_mul_f32 v[234:235], v[242:243], v[234:235] op_sel_hi:[0,1]
	v_pk_fma_f32 v[6:7], v[6:7], v[54:55], v[234:235] op_sel_hi:[1,0,1]
	v_pk_mul_f32 v[236:237], v[242:243], v[236:237] op_sel_hi:[0,1]
	v_cvt_pk_bf16_f32 v95, v6, s0
	v_pk_fma_f32 v[8:9], v[8:9], v[54:55], v[236:237] op_sel_hi:[1,0,1]
	ds_write_b16 v93, v95 offset:31776
	v_cvt_pk_bf16_f32 v95, v7, s0
	ds_write_b16 v93, v95 offset:31984
	v_cvt_pk_bf16_f32 v95, v8, s0
	ds_write_b16 v93, v95 offset:32192
	v_cvt_pk_bf16_f32 v95, v9, s0
	ds_write_b16 v93, v95 offset:32400
	ds_read_b64_tr_b16 v[234:235], v173 offset:13376
	ds_read_b64_tr_b16 v[236:237], v173 offset:14208
	ds_read_b64_tr_b16 v[238:239], v174 offset:13376
	ds_read_b64_tr_b16 v[240:241], v174 offset:14208
	s_waitcnt lgkmcnt(2)
	v_mfma_f32_16x16x32_bf16 v[198:201], v[198:201], v[234:237], 0
	s_waitcnt lgkmcnt(0)
	v_mfma_f32_16x16x32_bf16 v[198:201], v[202:205], v[238:241], v[198:201]
	s_nop 7
	v_pk_mul_f32 v[198:199], v[242:243], v[198:199] op_sel_hi:[0,1]
	v_pk_fma_f32 v[2:3], v[2:3], v[54:55], v[198:199] op_sel_hi:[1,0,1]
	v_pk_mul_f32 v[200:201], v[242:243], v[200:201] op_sel_hi:[0,1]
	v_cvt_pk_bf16_f32 v95, v2, s0
	v_pk_fma_f32 v[4:5], v[4:5], v[54:55], v[200:201] op_sel_hi:[1,0,1]
	ds_write_b16 v93, v95 offset:31808
	v_cvt_pk_bf16_f32 v95, v3, s0
	ds_write_b16 v93, v95 offset:32016
	v_cvt_pk_bf16_f32 v95, v4, s0
	ds_write_b16 v93, v95 offset:32224
	v_cvt_pk_bf16_f32 v95, v5, s0
	ds_write_b16 v93, v95 offset:32432
	s_nop 0
	s_and_b64 vcc, exec, s[60:61]
	s_cbranch_vccz .LBB0_552
	s_and_saveexec_b64 s[10:11], s[50:51]
	s_cbranch_execnz .LBB0_553

.Lwoff_ml_b:
	s_setprio 0
	s_and_b64 vcc, exec, s[28:29]
	s_cbranch_vccz .LBB0_561
	s_waitcnt vmcnt(6)
	v_lshl_add_u32 v14, v82, 1, v186
	v_ashrrev_i32_e32 v15, 31, v14
	v_lshlrev_b64 v[16:17], 8, v[14:15]
	v_or_b32_e32 v0, v16, v64
	s_waitcnt lgkmcnt(0)
	s_barrier
	s_waitcnt vmcnt(5)
	v_mad_u64_u32 v[18:19], s[10:11], v0, 48, s[12:13]
	v_mad_i32_i24 v19, v17, 48, v19
	v_lshlrev_b64 v[14:15], 9, v[14:15]
	global_store_dwordx4 v[18:19], v[10:13], off
	global_store_dwordx4 v[18:19], v[6:9], off offset:16
	global_store_dwordx4 v[18:19], v[2:5], off offset:32
	s_nop 1
	v_lshl_add_u64 v[2:3], s[8:9], 0, v[14:15]
	s_and_saveexec_b64 s[10:11], s[50:51]
	s_cbranch_execz .LBB0_558
	v_lshlrev_b32_e32 v0, 2, v64
	v_lshl_add_u64 v[4:5], v[2:3], 0, v[0:1]
	ds_read_b32 v0, v131 offset:46336
	s_waitcnt lgkmcnt(0)
	global_store_dword v[4:5], v0, off
